# G1: conv L2-norm reduction by DPP row ops (replaces 4 dependent ds_bpermute per token); G2 u double-buffered; P0 dt_bias/a_log constants hoisted
# baseline (speedup 1.0000x reference)
.LBB0_290:
	v_ashrrev_i32_e32 v188, 7, v210
	v_and_b32_e32 v211, 15, v210
	v_cmp_lt_i32_e32 vcc, 2, v188
	v_cmp_gt_i32_e64 s[38:39], 3, v188
	s_and_saveexec_b64 s[44:45], s[38:39]
	s_cbranch_execz .LBB0_308
	v_mov_b64_e32 v[58:59], v[218:219]
	v_mov_b64_e32 v[60:61], v[220:221]
	v_mov_b64_e32 v[46:47], v[222:223]
	v_mov_b64_e32 v[48:49], v[224:225]
	v_mov_b64_e32 v[62:63], v[226:227]
	v_mov_b64_e32 v[64:65], v[228:229]
	v_mov_b64_e32 v[50:51], v[230:231]
	v_mov_b64_e32 v[52:53], v[232:233]
	v_mov_b64_e32 v[70:71], v[234:235]
	v_mov_b64_e32 v[72:73], v[236:237]
	v_mov_b64_e32 v[54:55], v[238:239]
	v_mov_b64_e32 v[56:57], v[240:241]
	v_mov_b64_e32 v[74:75], v[248:249]
	v_mov_b64_e32 v[76:77], v[250:251]
	v_mov_b64_e32 v[66:67], v[252:253]
	v_mov_b64_e32 v[68:69], v[254:255]
	s_waitcnt vmcnt(11)
	v_lshlrev_b32_e32 v78, 16, v0
	v_and_b32_e32 v79, 0xffff0000, v0
	v_lshlrev_b32_e32 v102, 16, v4
	v_and_b32_e32 v103, 0xffff0000, v4
	v_lshlrev_b32_e32 v90, 16, v8
	v_and_b32_e32 v91, 0xffff0000, v8
	v_lshlrev_b32_e32 v100, 16, v12
	v_and_b32_e32 v101, 0xffff0000, v12
	v_lshlrev_b32_e32 v104, 16, v5
	v_and_b32_e32 v105, 0xffff0000, v5
	v_lshlrev_b32_e32 v86, 16, v9
	v_and_b32_e32 v87, 0xffff0000, v9
	v_lshlrev_b32_e32 v98, 16, v13
	v_and_b32_e32 v99, 0xffff0000, v13
	v_lshlrev_b32_e32 v106, 16, v6
	v_and_b32_e32 v107, 0xffff0000, v6
	v_lshlrev_b32_e32 v88, 16, v10
	v_and_b32_e32 v89, 0xffff0000, v10
	v_lshlrev_b32_e32 v96, 16, v14
	v_and_b32_e32 v97, 0xffff0000, v14
	v_lshlrev_b32_e32 v108, 16, v7
	v_and_b32_e32 v109, 0xffff0000, v7
	v_lshlrev_b32_e32 v92, 16, v11
	v_and_b32_e32 v93, 0xffff0000, v11
	v_lshlrev_b32_e32 v94, 16, v15
	v_and_b32_e32 v95, 0xffff0000, v15
	s_movk_i32 s8, 0x80
	v_cmp_gt_u32_e64 s[42:43], s8, v210
	v_cmp_ne_u32_e64 s[40:41], 2, v188
	v_pk_fma_f32 v[78:79], v[58:59], v[78:79], 0 op_sel_hi:[1,1,0]
	v_cndmask_b32_e64 v44, 1.0, v205, s[42:43]
	v_pk_fma_f32 v[78:79], v[62:63], v[102:103], v[78:79]
	s_nop 0
	v_pk_fma_f32 v[78:79], v[70:71], v[90:91], v[78:79]
	s_nop 0
	v_pk_fma_f32 v[78:79], v[74:75], v[100:101], v[78:79]
	s_nop 0
	v_mul_f32_e32 v80, 0xbfb8aa3b, v78
	v_mul_f32_e32 v81, 0xbfb8aa3b, v79
	v_exp_f32_e32 v80, v80
	v_exp_f32_e32 v81, v81
	v_add_f32_e32 v80, 1.0, v80
	v_add_f32_e32 v81, 1.0, v81
	v_rcp_f32_e32 v80, v80
	v_rcp_f32_e32 v81, v81
	s_nop 0
	v_pk_mul_f32 v[78:79], v[78:79], v[80:81]
	v_lshlrev_b32_e32 v80, 16, v1
	v_and_b32_e32 v81, 0xffff0000, v1
	v_pk_fma_f32 v[80:81], v[60:61], v[80:81], 0 op_sel_hi:[1,1,0]
	s_nop 0
	v_pk_fma_f32 v[80:81], v[64:65], v[104:105], v[80:81]
	s_nop 0
	v_pk_fma_f32 v[80:81], v[72:73], v[86:87], v[80:81]
	s_nop 0
	v_pk_fma_f32 v[80:81], v[76:77], v[98:99], v[80:81]
	s_nop 0
	v_mul_f32_e32 v82, 0xbfb8aa3b, v80
	v_mul_f32_e32 v83, 0xbfb8aa3b, v81
	v_exp_f32_e32 v82, v82
	v_exp_f32_e32 v83, v83
	v_add_f32_e32 v82, 1.0, v82
	v_add_f32_e32 v83, 1.0, v83
	v_rcp_f32_e32 v82, v82
	v_rcp_f32_e32 v83, v83
	s_nop 0
	v_pk_mul_f32 v[80:81], v[80:81], v[82:83]
	v_lshlrev_b32_e32 v82, 16, v2
	v_and_b32_e32 v83, 0xffff0000, v2
	v_pk_fma_f32 v[82:83], v[46:47], v[82:83], 0 op_sel_hi:[1,1,0]
	s_nop 0
	v_pk_fma_f32 v[82:83], v[50:51], v[106:107], v[82:83]
	s_nop 0
	v_pk_fma_f32 v[82:83], v[54:55], v[88:89], v[82:83]
	s_nop 0
	v_pk_fma_f32 v[82:83], v[66:67], v[96:97], v[82:83]
	s_nop 0
	v_mul_f32_e32 v84, 0xbfb8aa3b, v82
	v_mul_f32_e32 v85, 0xbfb8aa3b, v83
	v_exp_f32_e32 v84, v84
	v_exp_f32_e32 v85, v85
	v_add_f32_e32 v84, 1.0, v84
	v_add_f32_e32 v85, 1.0, v85
	v_rcp_f32_e32 v84, v84
	v_rcp_f32_e32 v85, v85
	s_nop 0
	v_pk_mul_f32 v[82:83], v[82:83], v[84:85]
	v_lshlrev_b32_e32 v84, 16, v3
	v_and_b32_e32 v85, 0xffff0000, v3
	v_pk_fma_f32 v[84:85], v[48:49], v[84:85], 0 op_sel_hi:[1,1,0]
	s_nop 0
	v_pk_fma_f32 v[84:85], v[52:53], v[108:109], v[84:85]
	s_nop 0
	v_pk_fma_f32 v[84:85], v[56:57], v[92:93], v[84:85]
	s_nop 0
	v_pk_fma_f32 v[84:85], v[68:69], v[94:95], v[84:85]
	s_nop 0
	v_mul_f32_e32 v110, 0xbfb8aa3b, v84
	v_mul_f32_e32 v111, 0xbfb8aa3b, v85
	v_exp_f32_e32 v110, v110
	v_exp_f32_e32 v111, v111
	v_add_f32_e32 v110, 1.0, v110
	v_add_f32_e32 v111, 1.0, v111
	v_rcp_f32_e32 v110, v110
	v_rcp_f32_e32 v111, v111
	s_nop 0
	v_pk_mul_f32 v[84:85], v[84:85], v[110:111]
	s_and_saveexec_b64 s[8:9], s[40:41]
	s_cbranch_execz .LBB0_293
	v_pk_mul_f32 v[110:111], v[78:79], v[78:79]
	v_pk_mul_f32 v[112:113], v[80:81], v[80:81]
	v_add_f32_e32 v110, v110, v111
	v_add_f32_e32 v110, v112, v110
	v_pk_mul_f32 v[114:115], v[82:83], v[82:83]
	v_add_f32_e32 v110, v113, v110
	v_add_f32_e32 v110, v114, v110
	v_pk_mul_f32 v[116:117], v[84:85], v[84:85]
	v_add_f32_e32 v110, v115, v110
	v_add_f32_e32 v110, v116, v110
	v_add_f32_e32 v110, v117, v110
	s_nop 1
	v_add_f32_dpp v110, v110, v110 quad_perm:[1,0,3,2] row_mask:0xf bank_mask:0xf
	s_nop 1
	v_add_f32_dpp v110, v110, v110 quad_perm:[2,3,0,1] row_mask:0xf bank_mask:0xf
	s_nop 1
	v_add_f32_dpp v110, v110, v110 row_half_mirror row_mask:0xf bank_mask:0xf
	s_nop 1
	v_add_f32_dpp v110, v110, v110 row_mirror row_mask:0xf bank_mask:0xf
	v_add_f32_e32 v110, 0x358637bd, v110
	v_rsq_f32_e32 v110, v110
	s_nop 0
	v_mul_f32_e32 v110, v44, v110
	v_pk_mul_f32 v[78:79], v[78:79], v[110:111] op_sel_hi:[1,0]
	v_pk_mul_f32 v[80:81], v[80:81], v[110:111] op_sel_hi:[1,0]
	v_pk_mul_f32 v[82:83], v[82:83], v[110:111] op_sel_hi:[1,0]
	v_pk_mul_f32 v[84:85], v[84:85], v[110:111] op_sel_hi:[1,0]
.LBB0_293:
	s_or_b64 exec, exec, s[8:9]
	v_pk_fma_f32 v[102:103], v[58:59], v[102:103], 0 op_sel_hi:[1,1,0]
	v_lshlrev_b32_e32 v138, 16, v16
	v_pk_fma_f32 v[102:103], v[62:63], v[90:91], v[102:103]
	v_and_b32_e32 v139, 0xffff0000, v16
	v_pk_fma_f32 v[102:103], v[70:71], v[100:101], v[102:103]
	v_pk_fma_f32 v[104:105], v[60:61], v[104:105], 0 op_sel_hi:[1,1,0]
	v_pk_fma_f32 v[102:103], v[74:75], v[138:139], v[102:103]
	v_pk_fma_f32 v[104:105], v[64:65], v[86:87], v[104:105]
	v_mul_f32_e32 v112, 0xbfb8aa3b, v102
	v_mul_f32_e32 v113, 0xbfb8aa3b, v103
	v_exp_f32_e32 v112, v112
	v_exp_f32_e32 v113, v113
	v_lshlrev_b32_e32 v124, 16, v17
	v_and_b32_e32 v125, 0xffff0000, v17
	v_add_f32_e32 v112, 1.0, v112
	v_add_f32_e32 v113, 1.0, v113
	v_rcp_f32_e32 v112, v112
	v_rcp_f32_e32 v113, v113
	v_pk_fma_f32 v[104:105], v[72:73], v[98:99], v[104:105]
	v_pk_fma_f32 v[106:107], v[46:47], v[106:107], 0 op_sel_hi:[1,1,0]
	v_pk_fma_f32 v[104:105], v[76:77], v[124:125], v[104:105]
	v_pk_mul_f32 v[102:103], v[102:103], v[112:113]
	v_mul_f32_e32 v112, 0xbfb8aa3b, v104
	v_mul_f32_e32 v113, 0xbfb8aa3b, v105
	v_exp_f32_e32 v112, v112
	v_exp_f32_e32 v113, v113
	v_pk_fma_f32 v[106:107], v[50:51], v[88:89], v[106:107]
	v_lshlrev_b32_e32 v118, 16, v18
	v_add_f32_e32 v112, 1.0, v112
	v_add_f32_e32 v113, 1.0, v113
	v_rcp_f32_e32 v112, v112
	v_rcp_f32_e32 v113, v113
	v_and_b32_e32 v119, 0xffff0000, v18
	v_pk_fma_f32 v[106:107], v[54:55], v[96:97], v[106:107]
	v_pk_fma_f32 v[108:109], v[48:49], v[108:109], 0 op_sel_hi:[1,1,0]
	v_pk_fma_f32 v[106:107], v[66:67], v[118:119], v[106:107]
	v_pk_mul_f32 v[104:105], v[104:105], v[112:113]
	v_mul_f32_e32 v112, 0xbfb8aa3b, v106
	v_mul_f32_e32 v113, 0xbfb8aa3b, v107
	v_exp_f32_e32 v112, v112
	v_exp_f32_e32 v113, v113
	v_pk_fma_f32 v[108:109], v[52:53], v[92:93], v[108:109]
	v_lshlrev_b32_e32 v110, 16, v19
	v_add_f32_e32 v112, 1.0, v112
	v_add_f32_e32 v113, 1.0, v113
	v_rcp_f32_e32 v112, v112
	v_rcp_f32_e32 v113, v113
	v_and_b32_e32 v111, 0xffff0000, v19
	v_pk_fma_f32 v[108:109], v[56:57], v[94:95], v[108:109]
	v_pk_mul_f32 v[106:107], v[106:107], v[112:113]
	v_pk_fma_f32 v[108:109], v[68:69], v[110:111], v[108:109]
	s_nop 0
	v_mul_f32_e32 v112, 0xbfb8aa3b, v108
	v_mul_f32_e32 v113, 0xbfb8aa3b, v109
	v_exp_f32_e32 v112, v112
	v_exp_f32_e32 v113, v113
	v_add_f32_e32 v112, 1.0, v112
	v_add_f32_e32 v113, 1.0, v113
	v_rcp_f32_e32 v112, v112
	v_rcp_f32_e32 v113, v113
	s_nop 0
	v_pk_mul_f32 v[108:109], v[108:109], v[112:113]
	s_and_saveexec_b64 s[8:9], s[40:41]
	s_cbranch_execz .LBB0_295
	v_pk_mul_f32 v[112:113], v[102:103], v[102:103]
	v_pk_mul_f32 v[114:115], v[104:105], v[104:105]
	v_add_f32_e32 v112, v112, v113
	v_add_f32_e32 v112, v114, v112
	v_pk_mul_f32 v[116:117], v[106:107], v[106:107]
	v_add_f32_e32 v112, v115, v112
	v_add_f32_e32 v112, v116, v112
	v_pk_mul_f32 v[120:121], v[108:109], v[108:109]
	v_add_f32_e32 v112, v117, v112
	v_add_f32_e32 v112, v120, v112
	v_add_f32_e32 v112, v121, v112
	s_nop 1
	v_add_f32_dpp v112, v112, v112 quad_perm:[1,0,3,2] row_mask:0xf bank_mask:0xf
	s_nop 1
	v_add_f32_dpp v112, v112, v112 quad_perm:[2,3,0,1] row_mask:0xf bank_mask:0xf
	s_nop 1
	v_add_f32_dpp v112, v112, v112 row_half_mirror row_mask:0xf bank_mask:0xf
	s_nop 1
	v_add_f32_dpp v112, v112, v112 row_mirror row_mask:0xf bank_mask:0xf
	v_add_f32_e32 v112, 0x358637bd, v112
	v_rsq_f32_e32 v112, v112
	s_nop 0
	v_mul_f32_e32 v112, v44, v112
	v_pk_mul_f32 v[102:103], v[102:103], v[112:113] op_sel_hi:[1,0]
	v_pk_mul_f32 v[104:105], v[104:105], v[112:113] op_sel_hi:[1,0]
	v_pk_mul_f32 v[106:107], v[106:107], v[112:113] op_sel_hi:[1,0]
	v_pk_mul_f32 v[108:109], v[108:109], v[112:113] op_sel_hi:[1,0]
.LBB0_295:
	s_or_b64 exec, exec, s[8:9]
	v_pk_fma_f32 v[90:91], v[58:59], v[90:91], 0 op_sel_hi:[1,1,0]
	v_lshlrev_b32_e32 v140, 16, v20
	v_pk_fma_f32 v[90:91], v[62:63], v[100:101], v[90:91]
	v_and_b32_e32 v141, 0xffff0000, v20
	v_pk_fma_f32 v[90:91], v[70:71], v[138:139], v[90:91]
	v_pk_fma_f32 v[86:87], v[60:61], v[86:87], 0 op_sel_hi:[1,1,0]
	v_pk_fma_f32 v[90:91], v[74:75], v[140:141], v[90:91]
	v_pk_fma_f32 v[86:87], v[64:65], v[98:99], v[86:87]
	v_mul_f32_e32 v114, 0xbfb8aa3b, v90
	v_mul_f32_e32 v115, 0xbfb8aa3b, v91
	v_exp_f32_e32 v114, v114
	v_exp_f32_e32 v115, v115
	v_lshlrev_b32_e32 v130, 16, v21
	v_and_b32_e32 v131, 0xffff0000, v21
	v_add_f32_e32 v114, 1.0, v114
	v_add_f32_e32 v115, 1.0, v115
	v_rcp_f32_e32 v114, v114
	v_rcp_f32_e32 v115, v115
	v_pk_fma_f32 v[86:87], v[72:73], v[124:125], v[86:87]
	v_pk_fma_f32 v[88:89], v[46:47], v[88:89], 0 op_sel_hi:[1,1,0]
	v_pk_fma_f32 v[86:87], v[76:77], v[130:131], v[86:87]
	v_pk_mul_f32 v[90:91], v[90:91], v[114:115]
	v_mul_f32_e32 v114, 0xbfb8aa3b, v86
	v_mul_f32_e32 v115, 0xbfb8aa3b, v87
	v_exp_f32_e32 v114, v114
	v_exp_f32_e32 v115, v115
	v_pk_fma_f32 v[88:89], v[50:51], v[96:97], v[88:89]
	v_lshlrev_b32_e32 v120, 16, v22
	v_add_f32_e32 v114, 1.0, v114
	v_add_f32_e32 v115, 1.0, v115
	v_rcp_f32_e32 v114, v114
	v_rcp_f32_e32 v115, v115
	v_and_b32_e32 v121, 0xffff0000, v22
	v_pk_fma_f32 v[88:89], v[54:55], v[118:119], v[88:89]
	v_pk_fma_f32 v[92:93], v[48:49], v[92:93], 0 op_sel_hi:[1,1,0]
	v_pk_fma_f32 v[88:89], v[66:67], v[120:121], v[88:89]
	v_pk_mul_f32 v[86:87], v[86:87], v[114:115]
	v_mul_f32_e32 v114, 0xbfb8aa3b, v88
	v_mul_f32_e32 v115, 0xbfb8aa3b, v89
	v_exp_f32_e32 v114, v114
	v_exp_f32_e32 v115, v115
	v_pk_fma_f32 v[92:93], v[52:53], v[94:95], v[92:93]
	v_lshlrev_b32_e32 v112, 16, v23
	v_add_f32_e32 v114, 1.0, v114
	v_add_f32_e32 v115, 1.0, v115
	v_rcp_f32_e32 v114, v114
	v_rcp_f32_e32 v115, v115
	v_and_b32_e32 v113, 0xffff0000, v23
	v_pk_fma_f32 v[92:93], v[56:57], v[110:111], v[92:93]
	v_pk_mul_f32 v[88:89], v[88:89], v[114:115]
	v_pk_fma_f32 v[92:93], v[68:69], v[112:113], v[92:93]
	s_nop 0
	v_mul_f32_e32 v114, 0xbfb8aa3b, v92
	v_mul_f32_e32 v115, 0xbfb8aa3b, v93
	v_exp_f32_e32 v114, v114
	v_exp_f32_e32 v115, v115
	v_add_f32_e32 v114, 1.0, v114
	v_add_f32_e32 v115, 1.0, v115
	v_rcp_f32_e32 v114, v114
	v_rcp_f32_e32 v115, v115
	s_nop 0
	v_pk_mul_f32 v[92:93], v[92:93], v[114:115]
	s_and_saveexec_b64 s[8:9], s[40:41]
	s_cbranch_execz .LBB0_297
	v_pk_mul_f32 v[114:115], v[90:91], v[90:91]
	v_pk_mul_f32 v[116:117], v[86:87], v[86:87]
	v_add_f32_e32 v114, v114, v115
	v_add_f32_e32 v114, v116, v114
	v_pk_mul_f32 v[122:123], v[88:89], v[88:89]
	v_add_f32_e32 v114, v117, v114
	v_add_f32_e32 v114, v122, v114
	v_pk_mul_f32 v[126:127], v[92:93], v[92:93]
	v_add_f32_e32 v114, v123, v114
	v_add_f32_e32 v114, v126, v114
	v_add_f32_e32 v114, v127, v114
	s_nop 1
	v_add_f32_dpp v114, v114, v114 quad_perm:[1,0,3,2] row_mask:0xf bank_mask:0xf
	s_nop 1
	v_add_f32_dpp v114, v114, v114 quad_perm:[2,3,0,1] row_mask:0xf bank_mask:0xf
	s_nop 1
	v_add_f32_dpp v114, v114, v114 row_half_mirror row_mask:0xf bank_mask:0xf
	s_nop 1
	v_add_f32_dpp v114, v114, v114 row_mirror row_mask:0xf bank_mask:0xf
	v_add_f32_e32 v114, 0x358637bd, v114
	v_rsq_f32_e32 v114, v114
	s_nop 0
	v_mul_f32_e32 v114, v44, v114
	v_pk_mul_f32 v[90:91], v[90:91], v[114:115] op_sel_hi:[1,0]
	v_pk_mul_f32 v[86:87], v[86:87], v[114:115] op_sel_hi:[1,0]
	v_pk_mul_f32 v[88:89], v[88:89], v[114:115] op_sel_hi:[1,0]
	v_pk_mul_f32 v[92:93], v[92:93], v[114:115] op_sel_hi:[1,0]
.LBB0_297:
	s_or_b64 exec, exec, s[8:9]
	v_pk_fma_f32 v[100:101], v[58:59], v[100:101], 0 op_sel_hi:[1,1,0]
	v_lshlrev_b32_e32 v136, 16, v24
	v_pk_fma_f32 v[100:101], v[62:63], v[138:139], v[100:101]
	v_and_b32_e32 v137, 0xffff0000, v24
	v_pk_fma_f32 v[100:101], v[70:71], v[140:141], v[100:101]
	v_pk_fma_f32 v[98:99], v[60:61], v[98:99], 0 op_sel_hi:[1,1,0]
	v_pk_fma_f32 v[100:101], v[74:75], v[136:137], v[100:101]
	v_pk_fma_f32 v[98:99], v[64:65], v[124:125], v[98:99]
	v_mul_f32_e32 v114, 0xbfb8aa3b, v100
	v_mul_f32_e32 v115, 0xbfb8aa3b, v101
	v_exp_f32_e32 v114, v114
	v_exp_f32_e32 v115, v115
	v_lshlrev_b32_e32 v134, 16, v25
	v_and_b32_e32 v135, 0xffff0000, v25
	v_add_f32_e32 v114, 1.0, v114
	v_add_f32_e32 v115, 1.0, v115
	v_rcp_f32_e32 v114, v114
	v_rcp_f32_e32 v115, v115
	v_pk_fma_f32 v[98:99], v[72:73], v[130:131], v[98:99]
	v_pk_fma_f32 v[96:97], v[46:47], v[96:97], 0 op_sel_hi:[1,1,0]
	v_pk_fma_f32 v[98:99], v[76:77], v[134:135], v[98:99]
	v_pk_mul_f32 v[114:115], v[100:101], v[114:115]
	v_mul_f32_e32 v100, 0xbfb8aa3b, v98
	v_mul_f32_e32 v101, 0xbfb8aa3b, v99
	v_exp_f32_e32 v100, v100
	v_exp_f32_e32 v101, v101
	v_pk_fma_f32 v[96:97], v[50:51], v[118:119], v[96:97]
	v_lshlrev_b32_e32 v132, 16, v26
	v_add_f32_e32 v100, 1.0, v100
	v_add_f32_e32 v101, 1.0, v101
	v_rcp_f32_e32 v100, v100
	v_rcp_f32_e32 v101, v101
	v_and_b32_e32 v133, 0xffff0000, v26
	v_pk_fma_f32 v[96:97], v[54:55], v[120:121], v[96:97]
	v_pk_fma_f32 v[94:95], v[48:49], v[94:95], 0 op_sel_hi:[1,1,0]
	v_pk_fma_f32 v[96:97], v[66:67], v[132:133], v[96:97]
	v_pk_mul_f32 v[116:117], v[98:99], v[100:101]
	v_mul_f32_e32 v98, 0xbfb8aa3b, v96
	v_mul_f32_e32 v99, 0xbfb8aa3b, v97
	v_exp_f32_e32 v98, v98
	v_exp_f32_e32 v99, v99
	v_pk_fma_f32 v[94:95], v[52:53], v[110:111], v[94:95]
	v_lshlrev_b32_e32 v122, 16, v27
	v_add_f32_e32 v98, 1.0, v98
	v_add_f32_e32 v99, 1.0, v99
	v_rcp_f32_e32 v98, v98
	v_rcp_f32_e32 v99, v99
	v_and_b32_e32 v123, 0xffff0000, v27
	v_pk_fma_f32 v[94:95], v[56:57], v[112:113], v[94:95]
	v_pk_mul_f32 v[126:127], v[96:97], v[98:99]
	v_pk_fma_f32 v[94:95], v[68:69], v[122:123], v[94:95]
	s_nop 0
	v_mul_f32_e32 v96, 0xbfb8aa3b, v94
	v_mul_f32_e32 v97, 0xbfb8aa3b, v95
	v_exp_f32_e32 v96, v96
	v_exp_f32_e32 v97, v97
	v_add_f32_e32 v96, 1.0, v96
	v_add_f32_e32 v97, 1.0, v97
	v_rcp_f32_e32 v96, v96
	v_rcp_f32_e32 v97, v97
	s_nop 0
	v_pk_mul_f32 v[128:129], v[94:95], v[96:97]
	s_and_saveexec_b64 s[8:9], s[40:41]
	s_cbranch_execz .LBB0_299
	v_pk_mul_f32 v[94:95], v[114:115], v[114:115]
	v_pk_mul_f32 v[96:97], v[116:117], v[116:117]
	v_add_f32_e32 v94, v94, v95
	v_add_f32_e32 v94, v96, v94
	v_pk_mul_f32 v[98:99], v[126:127], v[126:127]
	v_add_f32_e32 v94, v97, v94
	v_add_f32_e32 v94, v98, v94
	v_pk_mul_f32 v[100:101], v[128:129], v[128:129]
	v_add_f32_e32 v94, v99, v94
	v_add_f32_e32 v94, v100, v94
	v_add_f32_e32 v94, v101, v94
	s_nop 1
	v_add_f32_dpp v94, v94, v94 quad_perm:[1,0,3,2] row_mask:0xf bank_mask:0xf
	s_nop 1
	v_add_f32_dpp v94, v94, v94 quad_perm:[2,3,0,1] row_mask:0xf bank_mask:0xf
	s_nop 1
	v_add_f32_dpp v94, v94, v94 row_half_mirror row_mask:0xf bank_mask:0xf
	s_nop 1
	v_add_f32_dpp v94, v94, v94 row_mirror row_mask:0xf bank_mask:0xf
	v_add_f32_e32 v94, 0x358637bd, v94
	v_rsq_f32_e32 v94, v94
	s_nop 0
	v_mul_f32_e32 v94, v44, v94
	v_pk_mul_f32 v[114:115], v[114:115], v[94:95] op_sel_hi:[1,0]
	v_pk_mul_f32 v[116:117], v[116:117], v[94:95] op_sel_hi:[1,0]
	v_pk_mul_f32 v[126:127], v[126:127], v[94:95] op_sel_hi:[1,0]
	v_pk_mul_f32 v[128:129], v[128:129], v[94:95] op_sel_hi:[1,0]
.LBB0_299:
	s_or_b64 exec, exec, s[8:9]
	v_pk_fma_f32 v[94:95], v[58:59], v[138:139], 0 op_sel_hi:[1,1,0]
	v_lshlrev_b32_e32 v152, 16, v28
	v_and_b32_e32 v150, 0xffff0000, v28
	v_pk_fma_f32 v[94:95], v[62:63], v[140:141], v[94:95]
	v_mov_b32_e32 v156, v152
	v_pk_fma_f32 v[94:95], v[70:71], v[136:137], v[94:95]
	v_mov_b32_e32 v157, v150
	v_pk_fma_f32 v[94:95], v[74:75], v[156:157], v[94:95]
	v_lshlrev_b32_e32 v148, 16, v29
	v_mul_f32_e32 v96, 0xbfb8aa3b, v94
	v_mul_f32_e32 v97, 0xbfb8aa3b, v95
	v_exp_f32_e32 v96, v96
	v_exp_f32_e32 v97, v97
	v_and_b32_e32 v146, 0xffff0000, v29
	v_mov_b32_e32 v158, v148
	v_add_f32_e32 v96, 1.0, v96
	v_add_f32_e32 v97, 1.0, v97
	v_rcp_f32_e32 v96, v96
	v_rcp_f32_e32 v97, v97
	v_mov_b32_e32 v159, v146
	v_and_b32_e32 v145, 0xffff0000, v30
	v_lshlrev_b32_e32 v144, 16, v30
	v_pk_mul_f32 v[96:97], v[94:95], v[96:97]
	v_pk_fma_f32 v[94:95], v[60:61], v[124:125], 0 op_sel_hi:[1,1,0]
	v_and_b32_e32 v143, 0xffff0000, v31
	v_pk_fma_f32 v[94:95], v[64:65], v[130:131], v[94:95]
	v_lshlrev_b32_e32 v142, 16, v31
	v_pk_fma_f32 v[94:95], v[72:73], v[134:135], v[94:95]
	v_lshlrev_b32_e32 v153, 16, v32
	v_pk_fma_f32 v[94:95], v[76:77], v[158:159], v[94:95]
	v_and_b32_e32 v151, 0xffff0000, v32
	v_mul_f32_e32 v98, 0xbfb8aa3b, v94
	v_mul_f32_e32 v99, 0xbfb8aa3b, v95
	v_exp_f32_e32 v98, v98
	v_exp_f32_e32 v99, v99
	v_lshlrev_b32_e32 v149, 16, v33
	v_and_b32_e32 v147, 0xffff0000, v33
	v_add_f32_e32 v98, 1.0, v98
	v_add_f32_e32 v99, 1.0, v99
	v_rcp_f32_e32 v98, v98
	v_rcp_f32_e32 v99, v99
	s_nop 0
	v_pk_mul_f32 v[94:95], v[94:95], v[98:99]
	v_pk_fma_f32 v[98:99], v[46:47], v[118:119], 0 op_sel_hi:[1,1,0]
	s_nop 0
	v_pk_fma_f32 v[98:99], v[50:51], v[120:121], v[98:99]
	s_nop 0
	v_pk_fma_f32 v[98:99], v[54:55], v[132:133], v[98:99]
	s_nop 0
	v_pk_fma_f32 v[98:99], v[66:67], v[144:145], v[98:99]
	s_nop 0
	v_mul_f32_e32 v100, 0xbfb8aa3b, v98
	v_mul_f32_e32 v101, 0xbfb8aa3b, v99
	v_exp_f32_e32 v100, v100
	v_exp_f32_e32 v101, v101
	v_add_f32_e32 v100, 1.0, v100
	v_add_f32_e32 v101, 1.0, v101
	v_rcp_f32_e32 v100, v100
	v_rcp_f32_e32 v101, v101
	s_nop 0
	v_pk_mul_f32 v[98:99], v[98:99], v[100:101]
	v_pk_fma_f32 v[100:101], v[48:49], v[110:111], 0 op_sel_hi:[1,1,0]
	s_nop 0
	v_pk_fma_f32 v[100:101], v[52:53], v[112:113], v[100:101]
	s_nop 0
	v_pk_fma_f32 v[100:101], v[56:57], v[122:123], v[100:101]
	s_nop 0
	v_pk_fma_f32 v[100:101], v[68:69], v[142:143], v[100:101]
	s_nop 0
	v_mul_f32_e32 v110, 0xbfb8aa3b, v100
	v_mul_f32_e32 v111, 0xbfb8aa3b, v101
	v_exp_f32_e32 v110, v110
	v_exp_f32_e32 v111, v111
	v_add_f32_e32 v110, 1.0, v110
	v_add_f32_e32 v111, 1.0, v111
	v_rcp_f32_e32 v110, v110
	v_rcp_f32_e32 v111, v111
	s_nop 0
	v_pk_mul_f32 v[100:101], v[100:101], v[110:111]
	s_and_saveexec_b64 s[8:9], s[40:41]
	s_cbranch_execz .LBB0_301
	v_pk_mul_f32 v[110:111], v[96:97], v[96:97]
	v_pk_mul_f32 v[118:119], v[94:95], v[94:95]
	v_add_f32_e32 v110, v110, v111
	v_add_f32_e32 v110, v118, v110
	v_pk_mul_f32 v[124:125], v[98:99], v[98:99]
	v_add_f32_e32 v110, v119, v110
	v_add_f32_e32 v110, v124, v110
	v_pk_mul_f32 v[138:139], v[100:101], v[100:101]
	v_add_f32_e32 v110, v125, v110
	v_add_f32_e32 v110, v138, v110
	v_add_f32_e32 v110, v139, v110
	s_nop 1
	v_add_f32_dpp v110, v110, v110 quad_perm:[1,0,3,2] row_mask:0xf bank_mask:0xf
	s_nop 1
	v_add_f32_dpp v110, v110, v110 quad_perm:[2,3,0,1] row_mask:0xf bank_mask:0xf
	s_nop 1
	v_add_f32_dpp v110, v110, v110 row_half_mirror row_mask:0xf bank_mask:0xf
	s_nop 1
	v_add_f32_dpp v110, v110, v110 row_mirror row_mask:0xf bank_mask:0xf
	v_add_f32_e32 v110, 0x358637bd, v110
	v_rsq_f32_e32 v110, v110
	s_nop 0
	v_mul_f32_e32 v110, v44, v110
	v_pk_mul_f32 v[96:97], v[96:97], v[110:111] op_sel_hi:[1,0]
	v_pk_mul_f32 v[94:95], v[94:95], v[110:111] op_sel_hi:[1,0]
	v_pk_mul_f32 v[98:99], v[98:99], v[110:111] op_sel_hi:[1,0]
	v_pk_mul_f32 v[100:101], v[100:101], v[110:111] op_sel_hi:[1,0]
.LBB0_301:
	s_or_b64 exec, exec, s[8:9]
	v_pk_fma_f32 v[110:111], v[58:59], v[140:141], 0 op_sel_hi:[1,1,0]
	v_pk_fma_f32 v[130:131], v[60:61], v[130:131], 0 op_sel_hi:[1,1,0]
	v_pk_fma_f32 v[110:111], v[62:63], v[136:137], v[110:111]
	v_pk_fma_f32 v[130:131], v[64:65], v[134:135], v[130:131]
	v_pk_fma_f32 v[138:139], v[70:71], v[156:157], v[110:111]
	v_mov_b32_e32 v110, v153
	v_mov_b32_e32 v111, v151
	v_pk_fma_f32 v[138:139], v[74:75], v[110:111], v[138:139]
	v_pk_fma_f32 v[130:131], v[72:73], v[158:159], v[130:131]
	v_mul_f32_e32 v140, 0xbfb8aa3b, v138
	v_mul_f32_e32 v141, 0xbfb8aa3b, v139
	v_exp_f32_e32 v140, v140
	v_exp_f32_e32 v141, v141
	v_mov_b32_e32 v160, v149
	v_mov_b32_e32 v161, v147
	v_add_f32_e32 v140, 1.0, v140
	v_add_f32_e32 v141, 1.0, v141
	v_rcp_f32_e32 v140, v140
	v_rcp_f32_e32 v141, v141
	v_pk_fma_f32 v[130:131], v[76:77], v[160:161], v[130:131]
	v_pk_fma_f32 v[120:121], v[46:47], v[120:121], 0 op_sel_hi:[1,1,0]
	v_and_b32_e32 v125, 0xffff0000, v34
	v_pk_mul_f32 v[138:139], v[138:139], v[140:141]
	v_mul_f32_e32 v140, 0xbfb8aa3b, v130
	v_mul_f32_e32 v141, 0xbfb8aa3b, v131
	v_exp_f32_e32 v140, v140
	v_exp_f32_e32 v141, v141
	v_pk_fma_f32 v[120:121], v[50:51], v[132:133], v[120:121]
	v_lshlrev_b32_e32 v124, 16, v34
	v_add_f32_e32 v140, 1.0, v140
	v_add_f32_e32 v141, 1.0, v141
	v_rcp_f32_e32 v140, v140
	v_rcp_f32_e32 v141, v141
	v_pk_fma_f32 v[120:121], v[54:55], v[144:145], v[120:121]
	v_pk_fma_f32 v[112:113], v[48:49], v[112:113], 0 op_sel_hi:[1,1,0]
	v_pk_fma_f32 v[120:121], v[66:67], v[124:125], v[120:121]
	v_pk_mul_f32 v[140:141], v[130:131], v[140:141]
	v_mul_f32_e32 v130, 0xbfb8aa3b, v120
	v_mul_f32_e32 v131, 0xbfb8aa3b, v121
	v_exp_f32_e32 v130, v130
	v_exp_f32_e32 v131, v131
	v_pk_fma_f32 v[112:113], v[52:53], v[122:123], v[112:113]
	v_and_b32_e32 v119, 0xffff0000, v35
	v_add_f32_e32 v130, 1.0, v130
	v_add_f32_e32 v131, 1.0, v131
	v_rcp_f32_e32 v130, v130
	v_rcp_f32_e32 v131, v131
	v_lshlrev_b32_e32 v118, 16, v35
	v_pk_fma_f32 v[112:113], v[56:57], v[142:143], v[112:113]
	v_pk_mul_f32 v[154:155], v[120:121], v[130:131]
	v_pk_fma_f32 v[112:113], v[68:69], v[118:119], v[112:113]
	s_nop 0
	v_mul_f32_e32 v120, 0xbfb8aa3b, v112
	v_mul_f32_e32 v121, 0xbfb8aa3b, v113
	v_exp_f32_e32 v120, v120
	v_exp_f32_e32 v121, v121
	v_add_f32_e32 v120, 1.0, v120
	v_add_f32_e32 v121, 1.0, v121
	v_rcp_f32_e32 v120, v120
	v_rcp_f32_e32 v121, v121
	s_nop 0
	v_pk_mul_f32 v[130:131], v[112:113], v[120:121]
	s_and_saveexec_b64 s[8:9], s[40:41]
	s_cbranch_execz .LBB0_303
	v_pk_mul_f32 v[112:113], v[138:139], v[138:139]
	v_pk_mul_f32 v[120:121], v[140:141], v[140:141]
	v_add_f32_e32 v112, v112, v113
	v_add_f32_e32 v112, v120, v112
	v_pk_mul_f32 v[162:163], v[154:155], v[154:155]
	v_add_f32_e32 v112, v121, v112
	v_add_f32_e32 v112, v162, v112
	v_pk_mul_f32 v[164:165], v[130:131], v[130:131]
	v_add_f32_e32 v112, v163, v112
	v_add_f32_e32 v112, v164, v112
	v_add_f32_e32 v112, v165, v112
	s_nop 1
	v_add_f32_dpp v112, v112, v112 quad_perm:[1,0,3,2] row_mask:0xf bank_mask:0xf
	s_nop 1
	v_add_f32_dpp v112, v112, v112 quad_perm:[2,3,0,1] row_mask:0xf bank_mask:0xf
	s_nop 1
	v_add_f32_dpp v112, v112, v112 row_half_mirror row_mask:0xf bank_mask:0xf
	s_nop 1
	v_add_f32_dpp v112, v112, v112 row_mirror row_mask:0xf bank_mask:0xf
	v_add_f32_e32 v112, 0x358637bd, v112
	v_rsq_f32_e32 v112, v112
	s_nop 0
	v_mul_f32_e32 v112, v44, v112
	v_pk_mul_f32 v[138:139], v[138:139], v[112:113] op_sel_hi:[1,0]
	v_pk_mul_f32 v[140:141], v[140:141], v[112:113] op_sel_hi:[1,0]
	v_pk_mul_f32 v[154:155], v[154:155], v[112:113] op_sel_hi:[1,0]
	v_pk_mul_f32 v[130:131], v[130:131], v[112:113] op_sel_hi:[1,0]
.LBB0_303:
	s_or_b64 exec, exec, s[8:9]
	v_pk_fma_f32 v[132:133], v[46:47], v[132:133], 0 op_sel_hi:[1,1,0]
	v_and_b32_e32 v163, 0xffff0000, v38
	v_pk_fma_f32 v[132:133], v[50:51], v[144:145], v[132:133]
	v_lshlrev_b32_e32 v162, 16, v38
	v_pk_fma_f32 v[132:133], v[54:55], v[124:125], v[132:133]
	v_pk_fma_f32 v[112:113], v[58:59], v[136:137], 0 op_sel_hi:[1,1,0]
	v_pk_fma_f32 v[132:133], v[66:67], v[162:163], v[132:133]
	v_pk_fma_f32 v[112:113], v[62:63], v[156:157], v[112:113]
	v_mul_f32_e32 v156, 0xbfb8aa3b, v132
	v_exp_f32_e32 v156, v156
	v_mul_f32_e32 v157, 0xbfb8aa3b, v133
	v_exp_f32_e32 v157, v157
	v_pk_fma_f32 v[122:123], v[48:49], v[122:123], 0 op_sel_hi:[1,1,0]
	v_pk_fma_f32 v[134:135], v[60:61], v[134:135], 0 op_sel_hi:[1,1,0]
	v_pk_fma_f32 v[122:123], v[52:53], v[142:143], v[122:123]
	v_lshlrev_b32_e32 v170, 16, v36
	v_and_b32_e32 v168, 0xffff0000, v36
	v_lshlrev_b32_e32 v166, 16, v37
	v_and_b32_e32 v164, 0xffff0000, v37
	v_and_b32_e32 v121, 0xffff0000, v39
	v_lshlrev_b32_e32 v120, 16, v39
	v_pk_fma_f32 v[134:135], v[64:65], v[158:159], v[134:135]
	v_pk_fma_f32 v[122:123], v[56:57], v[118:119], v[122:123]
	v_pk_fma_f32 v[110:111], v[70:71], v[110:111], v[112:113]
	v_mov_b32_e32 v112, v170
	v_mov_b32_e32 v113, v168
	v_pk_fma_f32 v[134:135], v[72:73], v[160:161], v[134:135]
	v_mov_b32_e32 v136, v166
	v_mov_b32_e32 v137, v164
	v_add_f32_e32 v156, 1.0, v156
	v_pk_fma_f32 v[122:123], v[68:69], v[120:121], v[122:123]
	v_pk_fma_f32 v[110:111], v[74:75], v[112:113], v[110:111]
	v_pk_fma_f32 v[134:135], v[76:77], v[136:137], v[134:135]
	v_rcp_f32_e32 v158, v156
	v_add_f32_e32 v156, 1.0, v157
	v_mul_f32_e32 v157, 0xbfb8aa3b, v122
	v_mul_f32_e32 v112, 0xbfb8aa3b, v110
	v_mul_f32_e32 v113, 0xbfb8aa3b, v111
	v_mul_f32_e32 v136, 0xbfb8aa3b, v134
	v_mul_f32_e32 v137, 0xbfb8aa3b, v135
	v_exp_f32_e32 v157, v157
	v_mul_f32_e32 v159, 0xbfb8aa3b, v123
	v_exp_f32_e32 v112, v112
	v_exp_f32_e32 v113, v113
	v_exp_f32_e32 v136, v136
	v_exp_f32_e32 v137, v137
	v_exp_f32_e32 v161, v159
	v_rcp_f32_e32 v159, v156
	v_add_f32_e32 v156, 1.0, v157
	v_add_f32_e32 v112, 1.0, v112
	v_add_f32_e32 v113, 1.0, v113
	v_add_f32_e32 v136, 1.0, v136
	v_add_f32_e32 v137, 1.0, v137
	v_rcp_f32_e32 v160, v156
	v_add_f32_e32 v156, 1.0, v161
	v_rcp_f32_e32 v112, v112
	v_rcp_f32_e32 v113, v113
	v_rcp_f32_e32 v136, v136
	v_rcp_f32_e32 v137, v137
	v_rcp_f32_e32 v161, v156
	v_lshlrev_b32_e32 v171, 16, v40
	v_and_b32_e32 v169, 0xffff0000, v40
	v_lshlrev_b32_e32 v167, 16, v41
	v_and_b32_e32 v165, 0xffff0000, v41
	v_pk_mul_f32 v[156:157], v[110:111], v[112:113]
	v_pk_mul_f32 v[136:137], v[134:135], v[136:137]
	v_pk_mul_f32 v[112:113], v[132:133], v[158:159]
	v_pk_mul_f32 v[110:111], v[122:123], v[160:161]
	s_and_saveexec_b64 s[8:9], s[40:41]
	s_cbranch_execz .LBB0_305
	v_pk_mul_f32 v[122:123], v[156:157], v[156:157]
	v_pk_mul_f32 v[132:133], v[136:137], v[136:137]
	v_add_f32_e32 v122, v122, v123
	v_add_f32_e32 v122, v132, v122
	v_pk_mul_f32 v[134:135], v[112:113], v[112:113]
	v_add_f32_e32 v122, v133, v122
	v_add_f32_e32 v122, v134, v122
	v_pk_mul_f32 v[158:159], v[110:111], v[110:111]
	v_add_f32_e32 v122, v135, v122
	v_add_f32_e32 v122, v158, v122
	v_add_f32_e32 v122, v159, v122
	s_nop 1
	v_add_f32_dpp v122, v122, v122 quad_perm:[1,0,3,2] row_mask:0xf bank_mask:0xf
	s_nop 1
	v_add_f32_dpp v122, v122, v122 quad_perm:[2,3,0,1] row_mask:0xf bank_mask:0xf
	s_nop 1
	v_add_f32_dpp v122, v122, v122 row_half_mirror row_mask:0xf bank_mask:0xf
	s_nop 1
	v_add_f32_dpp v122, v122, v122 row_mirror row_mask:0xf bank_mask:0xf
	v_add_f32_e32 v122, 0x358637bd, v122
	v_rsq_f32_e32 v122, v122
	s_nop 0
	v_mul_f32_e32 v122, v44, v122
	v_pk_mul_f32 v[156:157], v[156:157], v[122:123] op_sel_hi:[1,0]
	v_pk_mul_f32 v[136:137], v[136:137], v[122:123] op_sel_hi:[1,0]
	v_pk_mul_f32 v[112:113], v[112:113], v[122:123] op_sel_hi:[1,0]
	v_pk_mul_f32 v[110:111], v[110:111], v[122:123] op_sel_hi:[1,0]
.LBB0_305:
	s_or_b64 exec, exec, s[8:9]
	v_mov_b32_e32 v122, v58
	v_mov_b32_e32 v123, v62
	v_pk_mul_f32 v[122:123], v[122:123], v[152:153]
	v_mov_b32_e32 v62, v59
	v_add_f32_e32 v58, 0, v122
	v_add_f32_e32 v58, v58, v123
	v_mov_b32_e32 v122, v70
	v_mov_b32_e32 v123, v74
	v_pk_mul_f32 v[122:123], v[122:123], v[170:171]
	v_mov_b32_e32 v74, v71
	v_add_f32_e32 v58, v58, v122
	v_add_f32_e32 v70, v58, v123
	v_mul_f32_e32 v58, 0xbfb8aa3b, v70
	v_exp_f32_e32 v58, v58
	v_pk_fma_f32 v[46:47], v[46:47], v[144:145], 0 op_sel_hi:[1,1,0]
	v_pk_fma_f32 v[48:49], v[48:49], v[142:143], 0 op_sel_hi:[1,1,0]
	v_pk_fma_f32 v[46:47], v[50:51], v[124:125], v[46:47]
	v_add_f32_e32 v58, 1.0, v58
	v_rcp_f32_e32 v132, v58
	v_pk_mul_f32 v[58:59], v[62:63], v[150:151]
	v_mov_b32_e32 v63, v64
	v_add_f32_e32 v58, 0, v58
	v_add_f32_e32 v62, v58, v59
	v_pk_mul_f32 v[58:59], v[74:75], v[168:169]
	v_mul_f32_e32 v71, v70, v132
	v_add_f32_e32 v58, v62, v58
	v_add_f32_e32 v74, v58, v59
	v_mul_f32_e32 v58, 0xbfb8aa3b, v74
	v_exp_f32_e32 v62, v58
	v_mov_b32_e32 v64, v61
	v_pk_fma_f32 v[48:49], v[52:53], v[118:119], v[48:49]
	v_and_b32_e32 v123, 0xffff0000, v42
	v_add_f32_e32 v62, 1.0, v62
	v_rcp_f32_e32 v70, v62
	v_mov_b32_e32 v62, v60
	v_pk_mul_f32 v[62:63], v[62:63], v[148:149]
	v_lshlrev_b32_e32 v122, 16, v42
	v_add_f32_e32 v60, 0, v62
	v_add_f32_e32 v60, v60, v63
	v_mov_b32_e32 v62, v72
	v_mov_b32_e32 v63, v76
	v_pk_mul_f32 v[62:63], v[62:63], v[166:167]
	v_mov_b32_e32 v76, v73
	v_add_f32_e32 v60, v60, v62
	v_add_f32_e32 v62, v60, v63
	v_mul_f32_e32 v60, 0xbfb8aa3b, v62
	v_exp_f32_e32 v63, v60
	v_pk_mul_f32 v[60:61], v[64:65], v[146:147]
	v_and_b32_e32 v59, 0xffff0000, v43
	v_add_f32_e32 v60, 0, v60
	v_add_f32_e32 v64, v60, v61
	v_pk_mul_f32 v[60:61], v[76:77], v[164:165]
	v_lshlrev_b32_e32 v58, 16, v43
	v_add_f32_e32 v60, v64, v60
	v_pk_fma_f32 v[46:47], v[54:55], v[162:163], v[46:47]
	v_pk_fma_f32 v[48:49], v[56:57], v[120:121], v[48:49]
	v_add_f32_e32 v60, v60, v61
	v_pk_fma_f32 v[46:47], v[66:67], v[122:123], v[46:47]
	v_pk_fma_f32 v[48:49], v[68:69], v[58:59], v[48:49]
	v_mul_f32_e32 v61, 0xbfb8aa3b, v60
	v_mul_f32_e32 v50, 0xbfb8aa3b, v46
	v_mul_f32_e32 v51, 0xbfb8aa3b, v47
	v_mul_f32_e32 v52, 0xbfb8aa3b, v48
	v_mul_f32_e32 v53, 0xbfb8aa3b, v49
	v_exp_f32_e32 v61, v61
	v_exp_f32_e32 v50, v50
	v_exp_f32_e32 v51, v51
	v_exp_f32_e32 v52, v52
	v_exp_f32_e32 v53, v53
	v_add_f32_e32 v63, 1.0, v63
	v_add_f32_e32 v61, 1.0, v61
	v_add_f32_e32 v50, 1.0, v50
	v_add_f32_e32 v51, 1.0, v51
	v_add_f32_e32 v52, 1.0, v52
	v_add_f32_e32 v53, 1.0, v53
	v_rcp_f32_e32 v63, v63
	v_rcp_f32_e32 v54, v61
	v_rcp_f32_e32 v50, v50
	v_rcp_f32_e32 v51, v51
	v_rcp_f32_e32 v52, v52
	v_rcp_f32_e32 v53, v53
	v_mul_f32_e32 v75, v74, v70
	v_mul_f32_e32 v77, v62, v63
	v_mul_f32_e32 v73, v60, v54
	v_pk_mul_f32 v[46:47], v[46:47], v[50:51]
	v_pk_mul_f32 v[48:49], v[48:49], v[52:53]
	s_and_saveexec_b64 s[8:9], s[40:41]
	s_cbranch_execz .LBB0_307
	v_mul_f32_e32 v52, v75, v75
	v_fmac_f32_e32 v52, v71, v71
	v_fmac_f32_e32 v52, v77, v77
	v_fmac_f32_e32 v52, v73, v73
	v_pk_mul_f32 v[50:51], v[46:47], v[46:47]
	s_nop 0
	v_add_f32_e32 v50, v50, v52
	v_add_f32_e32 v52, v51, v50
	v_pk_mul_f32 v[50:51], v[48:49], v[48:49]
	s_nop 0
	v_add_f32_e32 v50, v50, v52
	v_add_f32_e32 v50, v51, v50
	s_nop 1
	v_add_f32_dpp v50, v50, v50 quad_perm:[1,0,3,2] row_mask:0xf bank_mask:0xf
	s_nop 1
	v_add_f32_dpp v50, v50, v50 quad_perm:[2,3,0,1] row_mask:0xf bank_mask:0xf
	s_nop 1
	v_add_f32_dpp v50, v50, v50 row_half_mirror row_mask:0xf bank_mask:0xf
	s_nop 1
	v_add_f32_dpp v50, v50, v50 row_mirror row_mask:0xf bank_mask:0xf
	v_add_f32_e32 v50, 0x358637bd, v50
	v_rsq_f32_e32 v50, v50
	s_nop 0
	v_mul_f32_e32 v44, v44, v50
	v_mul_f32_e32 v71, v71, v44
	v_mul_f32_e32 v75, v75, v44
	v_mul_f32_e32 v77, v77, v44
	v_mul_f32_e32 v73, v73, v44
	v_mul_f32_e32 v46, v46, v44
	v_mul_f32_e32 v47, v47, v44
	v_mul_f32_e32 v48, v48, v44
	v_mul_f32_e32 v49, v49, v44
